# GEMM residual epilogues (L0 down, L1 out, L1 down): all 16 residual tile loads issued up front with counted vmcnt instead of load-wait-store per 16x8 piece
# speedup vs baseline: 1.0061x; 1.0026x over previous
; __device__ __forceinline__ unsigned cvt_pk_bf16(float lo, float hi) { unsigned r; asm volatile("v_cvt_pk_bf16_f32 %0, %1, %2" : "=v"(r) : "v"(lo), "v"(hi)); return r; }
;     __device__ __forceinline__ void operator()(const f32x4 (&acc)[2][2][4][2], const Unit& u, int wr, int wc, int fr, int fq) const {
;     ...
;         for (int ai = 0; ai < 2; ++ai)
; #pragma unroll
;             for (int m = 0; m < 4; ++m) { const size_t off = (size_t)(row0 + ai * HALF + m * 16) * ldc + col0;
; #pragma unroll
;                 for (int bj = 0; bj < 2; ++bj) { f32x4 r0, r1;
;                     if constexpr (sizeof(TI) == 4) { r0 = *(const f32x4*)((const float*)res + off + bj * HALF); r1 = *(const f32x4*)((const float*)res + off + bj * HALF + 4); }
;                     else { const u32x4 w = *(const u32x4*)((const bf16_t*)res + off + bj * HALF);
;                         r0 = (f32x4){__uint_as_float(w.x << 16), __uint_as_float(w.x & 0xffff0000u), __uint_as_float(w.y << 16), __uint_as_float(w.y & 0xffff0000u)};
;                         r1 = (f32x4){__uint_as_float(w.z << 16), __uint_as_float(w.z & 0xffff0000u), __uint_as_float(w.w << 16), __uint_as_float(w.w & 0xffff0000u)}; }
;                     const f32x4 o0 = r0 + gv[bj][0] * acc[ai][bj][m][0], o1 = r1 + gv[bj][1] * acc[ai][bj][m][1];
;                     if constexpr (sizeof(TO) == 4) { *(f32x4*)((float*)out + off + bj * HALF) = o0; *(f32x4*)((float*)out + off + bj * HALF + 4) = o1; }
;                     else { u32x4 w; w.x = cvt_pk_bf16(o0[0], o0[1]); w.y = cvt_pk_bf16(o0[2], o0[3]); w.z = cvt_pk_bf16(o1[0], o1[1]); w.w = cvt_pk_bf16(o1[2], o1[3]); *(u32x4*)((bf16_t*)out + off + bj * HALF) = w; } }
;                 asm volatile("" ::: "memory"); }
.LBB0_564:
	s_ashr_i32 s28, s73, 31
	v_lshl_add_u32 v162, s73, 8, v166
	v_lshl_or_b32 v120, s74, 8, v168
	s_lshr_b32 s28, s28, 28
	v_ashrrev_i32_e32 v163, 31, v162
	v_ashrrev_i32_e32 v121, 31, v120
	v_lshlrev_b64 v[122:123], 12, v[162:163]
	s_add_i32 s28, s73, s28
	v_lshl_add_u64 v[122:123], s[12:13], 0, v[122:123]
	v_lshlrev_b64 v[164:165], 1, v[120:121]
	s_ashr_i32 s28, s28, 4
	v_lshl_add_u64 v[160:161], v[122:123], 0, v[164:165]
	s_mul_hi_i32 s29, s28, 0xc000
	s_mul_i32 s28, s28, 0xc000
	global_load_dwordx4 v[172:175], v[160:161], off
	s_add_u32 s28, s60, s28
	s_addc_u32 s29, s61, s29
	v_lshl_add_u64 v[120:121], v[120:121], 2, s[28:29]
	global_load_dwordx4 v[132:135], v[120:121], off
	global_load_dwordx4 v[128:131], v[120:121], off offset:16
	global_load_dwordx4 v[124:127], v[120:121], off offset:512
	s_nop 0
	global_load_dwordx4 v[120:123], v[120:121], off offset:528
	global_load_dwordx4 v[180:183], v[160:161], off offset:256
	s_mov_b32 s92, 0x10000
	s_mov_b32 s93, 0
	v_lshl_add_u64 v[250:251], v[160:161], 0, s[92:93]
	global_load_dwordx4 v[184:187], v[250:251], off
	global_load_dwordx4 v[188:191], v[250:251], off offset:256
	s_mov_b32 s92, 0x20000
	s_mov_b32 s93, 0
	v_lshl_add_u64 v[250:251], v[160:161], 0, s[92:93]
	global_load_dwordx4 v[194:197], v[250:251], off
	global_load_dwordx4 v[198:201], v[250:251], off offset:256
	s_mov_b32 s92, 0x30000
	s_mov_b32 s93, 0
	v_lshl_add_u64 v[250:251], v[160:161], 0, s[92:93]
	global_load_dwordx4 v[202:205], v[250:251], off
	global_load_dwordx4 v[206:209], v[250:251], off offset:256
	s_mov_b32 s92, 0x80000
	s_mov_b32 s93, 0
	v_lshl_add_u64 v[250:251], v[160:161], 0, s[92:93]
	global_load_dwordx4 v[210:213], v[250:251], off
	global_load_dwordx4 v[214:217], v[250:251], off offset:256
	s_mov_b32 s92, 0x90000
	s_mov_b32 s93, 0
	v_lshl_add_u64 v[250:251], v[160:161], 0, s[92:93]
	global_load_dwordx4 v[226:229], v[250:251], off
	global_load_dwordx4 v[230:233], v[250:251], off offset:256
	s_mov_b32 s92, 0xa0000
	s_mov_b32 s93, 0
	v_lshl_add_u64 v[250:251], v[160:161], 0, s[92:93]
	global_load_dwordx4 v[234:237], v[250:251], off
	global_load_dwordx4 v[238:241], v[250:251], off offset:256
	s_mov_b32 s92, 0xb0000
	s_mov_b32 s93, 0
	v_lshl_add_u64 v[250:251], v[160:161], 0, s[92:93]
	global_load_dwordx4 v[242:245], v[250:251], off
	global_load_dwordx4 v[246:249], v[250:251], off offset:256
	s_waitcnt vmcnt(15)
	v_lshlrev_b32_e32 v176, 16, v172
	v_and_b32_e32 v177, 0xffff0000, v172
	v_lshlrev_b32_e32 v172, 16, v173
	v_and_b32_e32 v173, 0xffff0000, v173
	v_lshlrev_b32_e32 v178, 16, v174
	v_and_b32_e32 v179, 0xffff0000, v174
	v_lshlrev_b32_e32 v174, 16, v175
	v_and_b32_e32 v175, 0xffff0000, v175
	v_pk_fma_f32 v[142:143], v[142:143], v[134:135], v[172:173]
	v_pk_fma_f32 v[140:141], v[140:141], v[132:133], v[176:177]
	v_pk_fma_f32 v[172:173], v[138:139], v[130:131], v[174:175]
	v_pk_fma_f32 v[138:139], v[136:137], v[128:129], v[178:179]
	v_cvt_pk_bf16_f32 v136, v140, v141
	v_cvt_pk_bf16_f32 v137, v142, v143
	s_nop 0
	v_cvt_pk_bf16_f32 v138, v138, v139
	v_cvt_pk_bf16_f32 v139, v172, v173
	s_nop 0
	v_or_b32_e32 v172, 16, v162
	v_ashrrev_i32_e32 v173, 31, v172
	global_store_dwordx4 v[160:161], v[136:139], off
	v_lshlrev_b64 v[172:173], 12, v[172:173]
	v_lshl_add_u64 v[172:173], s[12:13], 0, v[172:173]
	v_lshl_add_u64 v[172:173], v[172:173], 0, v[164:165]
	s_waitcnt vmcnt(15)
	v_lshlrev_b32_e32 v136, 16, v180
	v_and_b32_e32 v137, 0xffff0000, v180
	v_lshlrev_b32_e32 v138, 16, v181
	v_and_b32_e32 v139, 0xffff0000, v181
	v_lshlrev_b32_e32 v140, 16, v182
	v_and_b32_e32 v141, 0xffff0000, v182
	v_lshlrev_b32_e32 v142, 16, v183
	v_and_b32_e32 v143, 0xffff0000, v183
	v_pk_fma_f32 v[116:117], v[116:117], v[124:125], v[136:137]
	v_pk_fma_f32 v[136:137], v[110:111], v[122:123], v[142:143]
	v_pk_fma_f32 v[110:111], v[108:109], v[120:121], v[140:141]
	v_pk_fma_f32 v[118:119], v[118:119], v[126:127], v[138:139]
	v_cvt_pk_bf16_f32 v108, v116, v117
	s_nop 0
	v_cvt_pk_bf16_f32 v109, v118, v119
	v_cvt_pk_bf16_f32 v110, v110, v111
	v_cvt_pk_bf16_f32 v111, v136, v137
	global_store_dwordx4 v[160:161], v[108:111], off offset:256
	s_nop 0
	s_waitcnt vmcnt(15)
	v_lshlrev_b32_e32 v116, 16, v184
	v_and_b32_e32 v117, 0xffff0000, v184
	v_lshlrev_b32_e32 v108, 16, v185
	v_and_b32_e32 v109, 0xffff0000, v185
	v_lshlrev_b32_e32 v118, 16, v186
	v_and_b32_e32 v119, 0xffff0000, v186
	v_lshlrev_b32_e32 v110, 16, v187
	v_and_b32_e32 v111, 0xffff0000, v187
	v_pk_fma_f32 v[108:109], v[114:115], v[134:135], v[108:109]
	v_pk_fma_f32 v[110:111], v[106:107], v[130:131], v[110:111]
	v_pk_fma_f32 v[106:107], v[104:105], v[128:129], v[118:119]
	v_pk_fma_f32 v[112:113], v[112:113], v[132:133], v[116:117]
	s_nop 0
	v_cvt_pk_bf16_f32 v104, v112, v113
	v_cvt_pk_bf16_f32 v105, v108, v109
	v_cvt_pk_bf16_f32 v106, v106, v107
	v_cvt_pk_bf16_f32 v107, v110, v111
	s_nop 0
	v_or_b32_e32 v112, 32, v162
	v_ashrrev_i32_e32 v113, 31, v112
	global_store_dwordx4 v[172:173], v[104:107], off
	v_lshlrev_b64 v[112:113], 12, v[112:113]
	v_lshl_add_u64 v[112:113], s[12:13], 0, v[112:113]
	v_lshl_add_u64 v[112:113], v[112:113], 0, v[164:165]
	s_waitcnt vmcnt(15)
	v_lshlrev_b32_e32 v104, 16, v188
	v_and_b32_e32 v105, 0xffff0000, v188
	v_lshlrev_b32_e32 v106, 16, v189
	v_and_b32_e32 v107, 0xffff0000, v189
	v_lshlrev_b32_e32 v108, 16, v190
	v_and_b32_e32 v109, 0xffff0000, v190
	v_lshlrev_b32_e32 v110, 16, v191
	v_and_b32_e32 v111, 0xffff0000, v191
	v_pk_fma_f32 v[100:101], v[100:101], v[124:125], v[104:105]
	v_pk_fma_f32 v[104:105], v[94:95], v[122:123], v[110:111]
	v_pk_fma_f32 v[94:95], v[92:93], v[120:121], v[108:109]
	v_pk_fma_f32 v[102:103], v[102:103], v[126:127], v[106:107]
	v_cvt_pk_bf16_f32 v92, v100, v101
	s_nop 0
	v_cvt_pk_bf16_f32 v93, v102, v103
	v_cvt_pk_bf16_f32 v94, v94, v95
	v_cvt_pk_bf16_f32 v95, v104, v105
	global_store_dwordx4 v[172:173], v[92:95], off offset:256
	s_nop 0
	s_waitcnt vmcnt(15)
; __device__ __forceinline__ unsigned cvt_pk_bf16(float lo, float hi) { unsigned r; asm volatile("v_cvt_pk_bf16_f32 %0, %1, %2" : "=v"(r) : "v"(lo), "v"(hi)); return r; }
;     __device__ __forceinline__ void operator()(const f32x4 (&acc)[2][2][4][2], const Unit& u, int wr, int wc, int fr, int fq) const {
;     ...
;         for (int ai = 0; ai < 2; ++ai)
; #pragma unroll
;             for (int m = 0; m < 4; ++m) { const size_t off = (size_t)(row0 + ai * HALF + m * 16) * ldc + col0;
; #pragma unroll
;                 for (int bj = 0; bj < 2; ++bj) { f32x4 r0, r1;
;                     if constexpr (sizeof(TI) == 4) { r0 = *(const f32x4*)((const float*)res + off + bj * HALF); r1 = *(const f32x4*)((const float*)res + off + bj * HALF + 4); }
;                     else { const u32x4 w = *(const u32x4*)((const bf16_t*)res + off + bj * HALF);
;                         r0 = (f32x4){__uint_as_float(w.x << 16), __uint_as_float(w.x & 0xffff0000u), __uint_as_float(w.y << 16), __uint_as_float(w.y & 0xffff0000u)};
;                         r1 = (f32x4){__uint_as_float(w.z << 16), __uint_as_float(w.z & 0xffff0000u), __uint_as_float(w.w << 16), __uint_as_float(w.w & 0xffff0000u)}; }
;                     const f32x4 o0 = r0 + gv[bj][0] * acc[ai][bj][m][0], o1 = r1 + gv[bj][1] * acc[ai][bj][m][1];
;                     if constexpr (sizeof(TO) == 4) { *(f32x4*)((float*)out + off + bj * HALF) = o0; *(f32x4*)((float*)out + off + bj * HALF + 4) = o1; }
;                     else { u32x4 w; w.x = cvt_pk_bf16(o0[0], o0[1]); w.y = cvt_pk_bf16(o0[2], o0[3]); w.z = cvt_pk_bf16(o1[0], o1[1]); w.w = cvt_pk_bf16(o1[2], o1[3]); *(u32x4*)((bf16_t*)out + off + bj * HALF) = w; } }
;                 asm volatile("" ::: "memory"); }
	v_lshlrev_b32_e32 v100, 16, v194
	v_and_b32_e32 v101, 0xffff0000, v194
	v_lshlrev_b32_e32 v92, 16, v195
	v_and_b32_e32 v93, 0xffff0000, v195
	v_lshlrev_b32_e32 v102, 16, v196
	v_and_b32_e32 v103, 0xffff0000, v196
	v_lshlrev_b32_e32 v94, 16, v197
	v_and_b32_e32 v95, 0xffff0000, v197
	v_pk_fma_f32 v[92:93], v[98:99], v[134:135], v[92:93]
	v_pk_fma_f32 v[94:95], v[90:91], v[130:131], v[94:95]
	v_pk_fma_f32 v[90:91], v[88:89], v[128:129], v[102:103]
	v_pk_fma_f32 v[96:97], v[96:97], v[132:133], v[100:101]
	s_nop 0
	v_cvt_pk_bf16_f32 v88, v96, v97
	v_cvt_pk_bf16_f32 v89, v92, v93
	v_cvt_pk_bf16_f32 v90, v90, v91
	v_cvt_pk_bf16_f32 v91, v94, v95
	s_nop 0
	v_or_b32_e32 v96, 48, v162
	v_ashrrev_i32_e32 v97, 31, v96
	global_store_dwordx4 v[112:113], v[88:91], off
	v_lshlrev_b64 v[96:97], 12, v[96:97]
	v_lshl_add_u64 v[96:97], s[12:13], 0, v[96:97]
	v_lshl_add_u64 v[96:97], v[96:97], 0, v[164:165]
	s_waitcnt vmcnt(15)
	v_lshlrev_b32_e32 v88, 16, v198
	v_and_b32_e32 v89, 0xffff0000, v198
	v_lshlrev_b32_e32 v90, 16, v199
	v_and_b32_e32 v91, 0xffff0000, v199
	v_lshlrev_b32_e32 v92, 16, v200
	v_and_b32_e32 v93, 0xffff0000, v200
	v_lshlrev_b32_e32 v94, 16, v201
	v_and_b32_e32 v95, 0xffff0000, v201
	v_pk_fma_f32 v[84:85], v[84:85], v[124:125], v[88:89]
	v_pk_fma_f32 v[88:89], v[78:79], v[122:123], v[94:95]
	v_pk_fma_f32 v[78:79], v[76:77], v[120:121], v[92:93]
	v_pk_fma_f32 v[86:87], v[86:87], v[126:127], v[90:91]
	v_cvt_pk_bf16_f32 v76, v84, v85
	s_nop 0
	v_cvt_pk_bf16_f32 v77, v86, v87
	v_cvt_pk_bf16_f32 v78, v78, v79
	v_cvt_pk_bf16_f32 v79, v88, v89
	global_store_dwordx4 v[112:113], v[76:79], off offset:256
	s_nop 0
	s_waitcnt vmcnt(15)
	v_lshlrev_b32_e32 v84, 16, v202
	v_and_b32_e32 v85, 0xffff0000, v202
	v_lshlrev_b32_e32 v76, 16, v203
	v_and_b32_e32 v77, 0xffff0000, v203
	v_lshlrev_b32_e32 v86, 16, v204
	v_and_b32_e32 v87, 0xffff0000, v204
	v_lshlrev_b32_e32 v78, 16, v205
	v_and_b32_e32 v79, 0xffff0000, v205
	v_pk_fma_f32 v[76:77], v[82:83], v[134:135], v[76:77]
	v_pk_fma_f32 v[78:79], v[74:75], v[130:131], v[78:79]
	v_pk_fma_f32 v[74:75], v[72:73], v[128:129], v[86:87]
	v_pk_fma_f32 v[80:81], v[80:81], v[132:133], v[84:85]
	s_nop 0
	v_cvt_pk_bf16_f32 v72, v80, v81
	v_cvt_pk_bf16_f32 v73, v76, v77
	v_cvt_pk_bf16_f32 v74, v74, v75
	v_cvt_pk_bf16_f32 v75, v78, v79
	s_nop 0
	v_add_co_u32_e32 v80, vcc, s67, v160
	global_store_dwordx4 v[96:97], v[72:75], off
	s_nop 0
	v_addc_co_u32_e32 v81, vcc, 0, v161, vcc
	s_waitcnt vmcnt(15)
	v_lshlrev_b32_e32 v72, 16, v206
	v_and_b32_e32 v73, 0xffff0000, v206
	v_lshlrev_b32_e32 v74, 16, v207
	v_and_b32_e32 v75, 0xffff0000, v207
	v_lshlrev_b32_e32 v76, 16, v208
	v_and_b32_e32 v77, 0xffff0000, v208
	v_lshlrev_b32_e32 v78, 16, v209
	v_and_b32_e32 v79, 0xffff0000, v209
	v_pk_fma_f32 v[68:69], v[68:69], v[124:125], v[72:73]
	v_pk_fma_f32 v[72:73], v[66:67], v[122:123], v[78:79]
	v_pk_fma_f32 v[66:67], v[64:65], v[120:121], v[76:77]
	v_pk_fma_f32 v[70:71], v[70:71], v[126:127], v[74:75]
	v_cvt_pk_bf16_f32 v64, v68, v69
	v_lshl_add_u64 v[68:69], v[160:161], 0, s[18:19]
	v_cvt_pk_bf16_f32 v65, v70, v71
	v_cvt_pk_bf16_f32 v66, v66, v67
	v_cvt_pk_bf16_f32 v67, v72, v73
	global_store_dwordx4 v[96:97], v[64:67], off offset:256
	s_nop 0
	s_waitcnt vmcnt(15)
	v_lshlrev_b32_e32 v70, 16, v210
	v_and_b32_e32 v71, 0xffff0000, v210
	v_lshlrev_b32_e32 v64, 16, v211
	v_and_b32_e32 v65, 0xffff0000, v211
	v_lshlrev_b32_e32 v72, 16, v212
	v_and_b32_e32 v73, 0xffff0000, v212
	v_lshlrev_b32_e32 v66, 16, v213
	v_and_b32_e32 v67, 0xffff0000, v213
	v_pk_fma_f32 v[62:63], v[62:63], v[134:135], v[64:65]
	v_pk_fma_f32 v[60:61], v[60:61], v[132:133], v[70:71]
	v_pk_fma_f32 v[64:65], v[58:59], v[130:131], v[66:67]
	v_pk_fma_f32 v[58:59], v[56:57], v[128:129], v[72:73]
	v_cvt_pk_bf16_f32 v56, v60, v61
	v_cvt_pk_bf16_f32 v57, v62, v63
	s_nop 0
	v_cvt_pk_bf16_f32 v58, v58, v59
	v_cvt_pk_bf16_f32 v59, v64, v65
	s_nop 0
	v_add_co_u32_e32 v64, vcc, s68, v160
	global_store_dwordx4 v[80:81], v[56:59], off
	s_nop 0
	v_addc_co_u32_e32 v65, vcc, 0, v161, vcc
	s_waitcnt vmcnt(15)
	v_lshlrev_b32_e32 v56, 16, v214
	v_and_b32_e32 v57, 0xffff0000, v214
	v_lshlrev_b32_e32 v58, 16, v215
	v_and_b32_e32 v59, 0xffff0000, v215
	v_lshlrev_b32_e32 v60, 16, v216
	v_and_b32_e32 v61, 0xffff0000, v216
	v_lshlrev_b32_e32 v62, 16, v217
	v_and_b32_e32 v63, 0xffff0000, v217
	v_pk_fma_f32 v[52:53], v[52:53], v[124:125], v[56:57]
	v_pk_fma_f32 v[56:57], v[46:47], v[122:123], v[62:63]
	v_pk_fma_f32 v[46:47], v[44:45], v[120:121], v[60:61]
	v_pk_fma_f32 v[54:55], v[54:55], v[126:127], v[58:59]
	v_cvt_pk_bf16_f32 v44, v52, v53
	v_lshl_add_u64 v[52:53], v[160:161], 0, s[20:21]
	v_cvt_pk_bf16_f32 v45, v54, v55
	v_cvt_pk_bf16_f32 v46, v46, v47
	v_cvt_pk_bf16_f32 v47, v56, v57
	global_store_dwordx4 v[68:69], v[44:47], off offset:256
	s_nop 0
	s_waitcnt vmcnt(15)
; __device__ __forceinline__ unsigned cvt_pk_bf16(float lo, float hi) { unsigned r; asm volatile("v_cvt_pk_bf16_f32 %0, %1, %2" : "=v"(r) : "v"(lo), "v"(hi)); return r; }
; #define PG8_BAR __builtin_amdgcn_s_barrier()
; template <class Epi, class Sched, bool ALIGN_EPI = false, bool SP2 = false>
; __device__ __forceinline__ void gemm_phase(PG8_LAS unsigned char* lds, const Gemm g, const Sched& S, const Epi& E) {
;     ...
;         if (!has_next) break;
; #pragma unroll
;         for (int a = 0; a < 2; ++a)
; #pragma unroll
;             for (int b = 0; b < 2; ++b)
; #pragma unroll
;                 for (int m = 0; m < 4; ++m)
; #pragma unroll
;                     for (int n = 0; n < 2; ++n) acc[a][b][m][n] = (f32x4){0.f, 0.f, 0.f, 0.f};
;         cur = nxt; cA = nA; cB = nB; ++ui;
;         if constexpr (ALIGN_EPI) { if (wr == 1) PG8_BAR; }
;     __device__ __forceinline__ void operator()(const f32x4 (&acc)[2][2][4][2], const Unit& u, int wr, int wc, int fr, int fq) const {
;     ...
;         for (int ai = 0; ai < 2; ++ai)
; #pragma unroll
;             for (int m = 0; m < 4; ++m) { const size_t off = (size_t)(row0 + ai * HALF + m * 16) * ldc + col0;
; #pragma unroll
;                 for (int bj = 0; bj < 2; ++bj) { f32x4 r0, r1;
;                     if constexpr (sizeof(TI) == 4) { r0 = *(const f32x4*)((const float*)res + off + bj * HALF); r1 = *(const f32x4*)((const float*)res + off + bj * HALF + 4); }
;                     else { const u32x4 w = *(const u32x4*)((const bf16_t*)res + off + bj * HALF);
;                         r0 = (f32x4){__uint_as_float(w.x << 16), __uint_as_float(w.x & 0xffff0000u), __uint_as_float(w.y << 16), __uint_as_float(w.y & 0xffff0000u)};
;                         r1 = (f32x4){__uint_as_float(w.z << 16), __uint_as_float(w.z & 0xffff0000u), __uint_as_float(w.w << 16), __uint_as_float(w.w & 0xffff0000u)}; }
;                     const f32x4 o0 = r0 + gv[bj][0] * acc[ai][bj][m][0], o1 = r1 + gv[bj][1] * acc[ai][bj][m][1];
;                     if constexpr (sizeof(TO) == 4) { *(f32x4*)((float*)out + off + bj * HALF) = o0; *(f32x4*)((float*)out + off + bj * HALF + 4) = o1; }
;                     else { u32x4 w; w.x = cvt_pk_bf16(o0[0], o0[1]); w.y = cvt_pk_bf16(o0[2], o0[3]); w.z = cvt_pk_bf16(o1[0], o1[1]); w.w = cvt_pk_bf16(o1[2], o1[3]); *(u32x4*)((bf16_t*)out + off + bj * HALF) = w; } }
;                 asm volatile("" ::: "memory"); }
	v_lshlrev_b32_e32 v54, 16, v226
	v_and_b32_e32 v55, 0xffff0000, v226
	v_lshlrev_b32_e32 v44, 16, v227
	v_and_b32_e32 v45, 0xffff0000, v227
	v_lshlrev_b32_e32 v56, 16, v228
	v_and_b32_e32 v57, 0xffff0000, v228
	v_lshlrev_b32_e32 v46, 16, v229
	v_and_b32_e32 v47, 0xffff0000, v229
	v_pk_fma_f32 v[44:45], v[50:51], v[134:135], v[44:45]
	v_pk_fma_f32 v[46:47], v[42:43], v[130:131], v[46:47]
	v_pk_fma_f32 v[42:43], v[40:41], v[128:129], v[56:57]
	v_pk_fma_f32 v[48:49], v[48:49], v[132:133], v[54:55]
	s_nop 0
	v_cvt_pk_bf16_f32 v40, v48, v49
	v_cvt_pk_bf16_f32 v41, v44, v45
	v_cvt_pk_bf16_f32 v42, v42, v43
	v_cvt_pk_bf16_f32 v43, v46, v47
	s_nop 0
	v_add_co_u32_e32 v48, vcc, s69, v160
	global_store_dwordx4 v[64:65], v[40:43], off
	s_nop 0
	v_addc_co_u32_e32 v49, vcc, 0, v161, vcc
	s_waitcnt vmcnt(15)
	v_lshlrev_b32_e32 v40, 16, v230
	v_and_b32_e32 v41, 0xffff0000, v230
	v_lshlrev_b32_e32 v42, 16, v231
	v_and_b32_e32 v43, 0xffff0000, v231
	v_lshlrev_b32_e32 v44, 16, v232
	v_and_b32_e32 v45, 0xffff0000, v232
	v_lshlrev_b32_e32 v46, 16, v233
	v_and_b32_e32 v47, 0xffff0000, v233
	v_pk_fma_f32 v[36:37], v[36:37], v[124:125], v[40:41]
	v_pk_fma_f32 v[40:41], v[30:31], v[122:123], v[46:47]
	v_pk_fma_f32 v[30:31], v[28:29], v[120:121], v[44:45]
	v_pk_fma_f32 v[38:39], v[38:39], v[126:127], v[42:43]
	v_cvt_pk_bf16_f32 v28, v36, v37
	v_lshl_add_u64 v[36:37], v[160:161], 0, s[22:23]
	v_cvt_pk_bf16_f32 v29, v38, v39
	v_cvt_pk_bf16_f32 v30, v30, v31
	v_cvt_pk_bf16_f32 v31, v40, v41
	global_store_dwordx4 v[52:53], v[28:31], off offset:256
	s_nop 0
	s_waitcnt vmcnt(15)
	v_lshlrev_b32_e32 v38, 16, v234
	v_and_b32_e32 v39, 0xffff0000, v234
	v_lshlrev_b32_e32 v28, 16, v235
	v_and_b32_e32 v29, 0xffff0000, v235
	v_lshlrev_b32_e32 v40, 16, v236
	v_and_b32_e32 v41, 0xffff0000, v236
	v_lshlrev_b32_e32 v30, 16, v237
	v_and_b32_e32 v31, 0xffff0000, v237
	v_pk_fma_f32 v[28:29], v[34:35], v[134:135], v[28:29]
	v_pk_fma_f32 v[30:31], v[26:27], v[130:131], v[30:31]
	v_pk_fma_f32 v[26:27], v[24:25], v[128:129], v[40:41]
	v_pk_fma_f32 v[32:33], v[32:33], v[132:133], v[38:39]
	s_nop 0
	v_cvt_pk_bf16_f32 v24, v32, v33
	v_cvt_pk_bf16_f32 v25, v28, v29
	v_cvt_pk_bf16_f32 v26, v26, v27
	v_cvt_pk_bf16_f32 v27, v30, v31
	s_nop 0
	v_add_co_u32_e32 v32, vcc, s70, v160
	global_store_dwordx4 v[48:49], v[24:27], off
	s_nop 0
	v_addc_co_u32_e32 v33, vcc, 0, v161, vcc
	s_and_b64 vcc, exec, s[6:7]
	s_mov_b64 s[6:7], -1
	s_waitcnt vmcnt(15)
	v_lshlrev_b32_e32 v24, 16, v238
	v_and_b32_e32 v25, 0xffff0000, v238
	v_lshlrev_b32_e32 v26, 16, v239
	v_and_b32_e32 v27, 0xffff0000, v239
	v_lshlrev_b32_e32 v28, 16, v240
	v_and_b32_e32 v29, 0xffff0000, v240
	v_lshlrev_b32_e32 v30, 16, v241
	v_and_b32_e32 v31, 0xffff0000, v241
	v_pk_fma_f32 v[20:21], v[20:21], v[124:125], v[24:25]
	v_pk_fma_f32 v[24:25], v[14:15], v[122:123], v[30:31]
	v_pk_fma_f32 v[14:15], v[12:13], v[120:121], v[28:29]
	v_pk_fma_f32 v[22:23], v[22:23], v[126:127], v[26:27]
	v_cvt_pk_bf16_f32 v12, v20, v21
	v_lshl_add_u64 v[20:21], v[160:161], 0, s[24:25]
	v_cvt_pk_bf16_f32 v13, v22, v23
	v_cvt_pk_bf16_f32 v14, v14, v15
	v_cvt_pk_bf16_f32 v15, v24, v25
	global_store_dwordx4 v[36:37], v[12:15], off offset:256
	s_nop 0
	s_waitcnt vmcnt(15)
	v_lshlrev_b32_e32 v22, 16, v242
	v_and_b32_e32 v23, 0xffff0000, v242
	v_lshlrev_b32_e32 v12, 16, v243
	v_and_b32_e32 v13, 0xffff0000, v243
	v_lshlrev_b32_e32 v24, 16, v244
	v_and_b32_e32 v25, 0xffff0000, v244
	v_lshlrev_b32_e32 v14, 16, v245
	v_and_b32_e32 v15, 0xffff0000, v245
	v_pk_fma_f32 v[12:13], v[18:19], v[134:135], v[12:13]
	v_pk_fma_f32 v[14:15], v[10:11], v[130:131], v[14:15]
	v_pk_fma_f32 v[10:11], v[8:9], v[128:129], v[24:25]
	v_pk_fma_f32 v[16:17], v[16:17], v[132:133], v[22:23]
	s_nop 0
	v_cvt_pk_bf16_f32 v8, v16, v17
	v_cvt_pk_bf16_f32 v9, v12, v13
	v_cvt_pk_bf16_f32 v10, v10, v11
	v_cvt_pk_bf16_f32 v11, v14, v15
	s_nop 0
	s_nop 0
	global_store_dwordx4 v[32:33], v[8:11], off
	s_waitcnt vmcnt(15)
	s_nop 0
	v_lshlrev_b32_e32 v8, 16, v246
	v_and_b32_e32 v9, 0xffff0000, v246
	v_lshlrev_b32_e32 v10, 16, v247
	v_and_b32_e32 v11, 0xffff0000, v247
	v_lshlrev_b32_e32 v12, 16, v248
	v_and_b32_e32 v13, 0xffff0000, v248
	v_lshlrev_b32_e32 v14, 16, v249
	v_and_b32_e32 v15, 0xffff0000, v249
	v_pk_fma_f32 v[4:5], v[4:5], v[124:125], v[8:9]
	v_pk_fma_f32 v[8:9], v[2:3], v[122:123], v[14:15]
	v_pk_fma_f32 v[2:3], v[0:1], v[120:121], v[12:13]
	v_pk_fma_f32 v[6:7], v[6:7], v[126:127], v[10:11]
	v_cvt_pk_bf16_f32 v0, v4, v5
	s_nop 0
	v_cvt_pk_bf16_f32 v1, v6, v7
	v_cvt_pk_bf16_f32 v2, v2, v3
	v_cvt_pk_bf16_f32 v3, v8, v9
	global_store_dwordx4 v[20:21], v[0:3], off offset:256
	s_cbranch_vccnz .LBB0_549
	s_andn2_b64 vcc, exec, s[10:11]
	s_cbranch_vccnz .LBB0_548
	s_barrier
	s_branch .LBB0_548

; __device__ __forceinline__ unsigned cvt_pk_bf16(float lo, float hi) { unsigned r; asm volatile("v_cvt_pk_bf16_f32 %0, %1, %2" : "=v"(r) : "v"(lo), "v"(hi)); return r; }
;     __device__ __forceinline__ void operator()(const f32x4 (&acc)[2][2][4][2], const Unit& u, int wr, int wc, int fr, int fq) const {
;     ...
;         for (int ai = 0; ai < 2; ++ai)
; #pragma unroll
;             for (int m = 0; m < 4; ++m) { const size_t off = (size_t)(row0 + ai * HALF + m * 16) * ldc + col0;
; #pragma unroll
;                 for (int bj = 0; bj < 2; ++bj) { f32x4 r0, r1;
;                     if constexpr (sizeof(TI) == 4) { r0 = *(const f32x4*)((const float*)res + off + bj * HALF); r1 = *(const f32x4*)((const float*)res + off + bj * HALF + 4); }
;                     else { const u32x4 w = *(const u32x4*)((const bf16_t*)res + off + bj * HALF);
;                         r0 = (f32x4){__uint_as_float(w.x << 16), __uint_as_float(w.x & 0xffff0000u), __uint_as_float(w.y << 16), __uint_as_float(w.y & 0xffff0000u)};
;                         r1 = (f32x4){__uint_as_float(w.z << 16), __uint_as_float(w.z & 0xffff0000u), __uint_as_float(w.w << 16), __uint_as_float(w.w & 0xffff0000u)}; }
;                     const f32x4 o0 = r0 + gv[bj][0] * acc[ai][bj][m][0], o1 = r1 + gv[bj][1] * acc[ai][bj][m][1];
;                     if constexpr (sizeof(TO) == 4) { *(f32x4*)((float*)out + off + bj * HALF) = o0; *(f32x4*)((float*)out + off + bj * HALF + 4) = o1; }
;                     else { u32x4 w; w.x = cvt_pk_bf16(o0[0], o0[1]); w.y = cvt_pk_bf16(o0[2], o0[3]); w.z = cvt_pk_bf16(o1[0], o1[1]); w.w = cvt_pk_bf16(o1[2], o1[3]); *(u32x4*)((bf16_t*)out + off + bj * HALF) = w; } }
;                 asm volatile("" ::: "memory"); }
.LBB0_1045:
	s_ashr_i32 s25, s34, 31
	v_lshl_add_u32 v162, s34, 8, v166
	v_lshl_or_b32 v120, s36, 8, v168
	s_lshr_b32 s25, s25, 28
	v_ashrrev_i32_e32 v163, 31, v162
	v_ashrrev_i32_e32 v121, 31, v120
	v_lshlrev_b64 v[122:123], 12, v[162:163]
	s_add_i32 s25, s34, s25
	v_lshl_add_u64 v[122:123], s[12:13], 0, v[122:123]
	v_lshlrev_b64 v[164:165], 1, v[120:121]
	s_ashr_i32 s25, s25, 4
	v_lshl_add_u64 v[160:161], v[122:123], 0, v[164:165]
	s_mul_hi_i32 s27, s25, 0xc000
	s_mul_i32 s25, s25, 0xc000
	global_load_dwordx4 v[172:175], v[160:161], off
	s_add_u32 s46, s62, s25
	s_addc_u32 s47, s63, s27
	v_lshl_add_u64 v[120:121], v[120:121], 2, s[46:47]
	global_load_dwordx4 v[132:135], v[120:121], off
	global_load_dwordx4 v[128:131], v[120:121], off offset:16
	global_load_dwordx4 v[124:127], v[120:121], off offset:512
	s_nop 0
	global_load_dwordx4 v[120:123], v[120:121], off offset:528
	global_load_dwordx4 v[180:183], v[160:161], off offset:256
	s_mov_b32 s92, 0x10000
	s_mov_b32 s93, 0
	v_lshl_add_u64 v[250:251], v[160:161], 0, s[92:93]
	global_load_dwordx4 v[184:187], v[250:251], off
	global_load_dwordx4 v[188:191], v[250:251], off offset:256
	s_mov_b32 s92, 0x20000
	s_mov_b32 s93, 0
	v_lshl_add_u64 v[250:251], v[160:161], 0, s[92:93]
	global_load_dwordx4 v[194:197], v[250:251], off
	global_load_dwordx4 v[198:201], v[250:251], off offset:256
	s_mov_b32 s92, 0x30000
	s_mov_b32 s93, 0
	v_lshl_add_u64 v[250:251], v[160:161], 0, s[92:93]
	global_load_dwordx4 v[202:205], v[250:251], off
	global_load_dwordx4 v[206:209], v[250:251], off offset:256
	s_mov_b32 s92, 0x80000
	s_mov_b32 s93, 0
	v_lshl_add_u64 v[250:251], v[160:161], 0, s[92:93]
	global_load_dwordx4 v[210:213], v[250:251], off
	global_load_dwordx4 v[214:217], v[250:251], off offset:256
	s_mov_b32 s92, 0x90000
	s_mov_b32 s93, 0
	v_lshl_add_u64 v[250:251], v[160:161], 0, s[92:93]
	global_load_dwordx4 v[226:229], v[250:251], off
	global_load_dwordx4 v[230:233], v[250:251], off offset:256
	s_mov_b32 s92, 0xa0000
	s_mov_b32 s93, 0
	v_lshl_add_u64 v[250:251], v[160:161], 0, s[92:93]
	global_load_dwordx4 v[234:237], v[250:251], off
	global_load_dwordx4 v[238:241], v[250:251], off offset:256
	s_mov_b32 s92, 0xb0000
	s_mov_b32 s93, 0
	v_lshl_add_u64 v[250:251], v[160:161], 0, s[92:93]
	global_load_dwordx4 v[242:245], v[250:251], off
	global_load_dwordx4 v[246:249], v[250:251], off offset:256
	s_waitcnt vmcnt(15)
	v_lshlrev_b32_e32 v176, 16, v172
	v_and_b32_e32 v177, 0xffff0000, v172
	v_lshlrev_b32_e32 v172, 16, v173
	v_and_b32_e32 v173, 0xffff0000, v173
	v_lshlrev_b32_e32 v178, 16, v174
	v_and_b32_e32 v179, 0xffff0000, v174
	v_lshlrev_b32_e32 v174, 16, v175
	v_and_b32_e32 v175, 0xffff0000, v175
	v_pk_fma_f32 v[142:143], v[142:143], v[134:135], v[172:173]
	v_pk_fma_f32 v[140:141], v[140:141], v[132:133], v[176:177]
	v_pk_fma_f32 v[172:173], v[138:139], v[130:131], v[174:175]
	v_pk_fma_f32 v[138:139], v[136:137], v[128:129], v[178:179]
	v_cvt_pk_bf16_f32 v136, v140, v141
	v_cvt_pk_bf16_f32 v137, v142, v143
	s_nop 0
	v_cvt_pk_bf16_f32 v138, v138, v139
	v_cvt_pk_bf16_f32 v139, v172, v173
	s_nop 0
	v_or_b32_e32 v172, 16, v162
	v_ashrrev_i32_e32 v173, 31, v172
	global_store_dwordx4 v[160:161], v[136:139], off
	v_lshlrev_b64 v[172:173], 12, v[172:173]
	v_lshl_add_u64 v[172:173], s[12:13], 0, v[172:173]
	v_lshl_add_u64 v[172:173], v[172:173], 0, v[164:165]
	s_waitcnt vmcnt(15)
	v_lshlrev_b32_e32 v136, 16, v180
	v_and_b32_e32 v137, 0xffff0000, v180
	v_lshlrev_b32_e32 v138, 16, v181
	v_and_b32_e32 v139, 0xffff0000, v181
	v_lshlrev_b32_e32 v140, 16, v182
	v_and_b32_e32 v141, 0xffff0000, v182
	v_lshlrev_b32_e32 v142, 16, v183
	v_and_b32_e32 v143, 0xffff0000, v183
	v_pk_fma_f32 v[116:117], v[116:117], v[124:125], v[136:137]
	v_pk_fma_f32 v[136:137], v[110:111], v[122:123], v[142:143]
	v_pk_fma_f32 v[110:111], v[108:109], v[120:121], v[140:141]
	v_pk_fma_f32 v[118:119], v[118:119], v[126:127], v[138:139]
	v_cvt_pk_bf16_f32 v108, v116, v117
	s_nop 0
	v_cvt_pk_bf16_f32 v109, v118, v119
	v_cvt_pk_bf16_f32 v110, v110, v111
	v_cvt_pk_bf16_f32 v111, v136, v137
	global_store_dwordx4 v[160:161], v[108:111], off offset:256
	s_nop 0
	s_waitcnt vmcnt(15)
	v_lshlrev_b32_e32 v116, 16, v184
	v_and_b32_e32 v117, 0xffff0000, v184
	v_lshlrev_b32_e32 v108, 16, v185
	v_and_b32_e32 v109, 0xffff0000, v185
	v_lshlrev_b32_e32 v118, 16, v186
	v_and_b32_e32 v119, 0xffff0000, v186
	v_lshlrev_b32_e32 v110, 16, v187
	v_and_b32_e32 v111, 0xffff0000, v187
	v_pk_fma_f32 v[108:109], v[114:115], v[134:135], v[108:109]
	v_pk_fma_f32 v[110:111], v[106:107], v[130:131], v[110:111]
	v_pk_fma_f32 v[106:107], v[104:105], v[128:129], v[118:119]
	v_pk_fma_f32 v[112:113], v[112:113], v[132:133], v[116:117]
	s_nop 0
	v_cvt_pk_bf16_f32 v104, v112, v113
	v_cvt_pk_bf16_f32 v105, v108, v109
	v_cvt_pk_bf16_f32 v106, v106, v107
	v_cvt_pk_bf16_f32 v107, v110, v111
	s_nop 0
	v_or_b32_e32 v112, 32, v162
	v_ashrrev_i32_e32 v113, 31, v112
	global_store_dwordx4 v[172:173], v[104:107], off
	v_lshlrev_b64 v[112:113], 12, v[112:113]
	v_lshl_add_u64 v[112:113], s[12:13], 0, v[112:113]
	v_lshl_add_u64 v[112:113], v[112:113], 0, v[164:165]
	s_waitcnt vmcnt(15)
	v_lshlrev_b32_e32 v104, 16, v188
	v_and_b32_e32 v105, 0xffff0000, v188
	v_lshlrev_b32_e32 v106, 16, v189
	v_and_b32_e32 v107, 0xffff0000, v189
	v_lshlrev_b32_e32 v108, 16, v190
	v_and_b32_e32 v109, 0xffff0000, v190
	v_lshlrev_b32_e32 v110, 16, v191
	v_and_b32_e32 v111, 0xffff0000, v191
	v_pk_fma_f32 v[100:101], v[100:101], v[124:125], v[104:105]
	v_pk_fma_f32 v[104:105], v[94:95], v[122:123], v[110:111]
	v_pk_fma_f32 v[94:95], v[92:93], v[120:121], v[108:109]
	v_pk_fma_f32 v[102:103], v[102:103], v[126:127], v[106:107]
	v_cvt_pk_bf16_f32 v92, v100, v101
	s_nop 0
	v_cvt_pk_bf16_f32 v93, v102, v103
	v_cvt_pk_bf16_f32 v94, v94, v95
	v_cvt_pk_bf16_f32 v95, v104, v105
	global_store_dwordx4 v[172:173], v[92:95], off offset:256
	s_nop 0
	s_waitcnt vmcnt(15)
; __device__ __forceinline__ unsigned cvt_pk_bf16(float lo, float hi) { unsigned r; asm volatile("v_cvt_pk_bf16_f32 %0, %1, %2" : "=v"(r) : "v"(lo), "v"(hi)); return r; }
;     __device__ __forceinline__ void operator()(const f32x4 (&acc)[2][2][4][2], const Unit& u, int wr, int wc, int fr, int fq) const {
;     ...
;         for (int ai = 0; ai < 2; ++ai)
; #pragma unroll
;             for (int m = 0; m < 4; ++m) { const size_t off = (size_t)(row0 + ai * HALF + m * 16) * ldc + col0;
; #pragma unroll
;                 for (int bj = 0; bj < 2; ++bj) { f32x4 r0, r1;
;                     if constexpr (sizeof(TI) == 4) { r0 = *(const f32x4*)((const float*)res + off + bj * HALF); r1 = *(const f32x4*)((const float*)res + off + bj * HALF + 4); }
;                     else { const u32x4 w = *(const u32x4*)((const bf16_t*)res + off + bj * HALF);
;                         r0 = (f32x4){__uint_as_float(w.x << 16), __uint_as_float(w.x & 0xffff0000u), __uint_as_float(w.y << 16), __uint_as_float(w.y & 0xffff0000u)};
;                         r1 = (f32x4){__uint_as_float(w.z << 16), __uint_as_float(w.z & 0xffff0000u), __uint_as_float(w.w << 16), __uint_as_float(w.w & 0xffff0000u)}; }
;                     const f32x4 o0 = r0 + gv[bj][0] * acc[ai][bj][m][0], o1 = r1 + gv[bj][1] * acc[ai][bj][m][1];
;                     if constexpr (sizeof(TO) == 4) { *(f32x4*)((float*)out + off + bj * HALF) = o0; *(f32x4*)((float*)out + off + bj * HALF + 4) = o1; }
;                     else { u32x4 w; w.x = cvt_pk_bf16(o0[0], o0[1]); w.y = cvt_pk_bf16(o0[2], o0[3]); w.z = cvt_pk_bf16(o1[0], o1[1]); w.w = cvt_pk_bf16(o1[2], o1[3]); *(u32x4*)((bf16_t*)out + off + bj * HALF) = w; } }
;                 asm volatile("" ::: "memory"); }
	v_lshlrev_b32_e32 v100, 16, v194
	v_and_b32_e32 v101, 0xffff0000, v194
	v_lshlrev_b32_e32 v92, 16, v195
	v_and_b32_e32 v93, 0xffff0000, v195
	v_lshlrev_b32_e32 v102, 16, v196
	v_and_b32_e32 v103, 0xffff0000, v196
	v_lshlrev_b32_e32 v94, 16, v197
	v_and_b32_e32 v95, 0xffff0000, v197
	v_pk_fma_f32 v[92:93], v[98:99], v[134:135], v[92:93]
	v_pk_fma_f32 v[94:95], v[90:91], v[130:131], v[94:95]
	v_pk_fma_f32 v[90:91], v[88:89], v[128:129], v[102:103]
	v_pk_fma_f32 v[96:97], v[96:97], v[132:133], v[100:101]
	s_nop 0
	v_cvt_pk_bf16_f32 v88, v96, v97
	v_cvt_pk_bf16_f32 v89, v92, v93
	v_cvt_pk_bf16_f32 v90, v90, v91
	v_cvt_pk_bf16_f32 v91, v94, v95
	s_nop 0
	v_or_b32_e32 v96, 48, v162
	v_ashrrev_i32_e32 v97, 31, v96
	global_store_dwordx4 v[112:113], v[88:91], off
	v_lshlrev_b64 v[96:97], 12, v[96:97]
	v_lshl_add_u64 v[96:97], s[12:13], 0, v[96:97]
	v_lshl_add_u64 v[96:97], v[96:97], 0, v[164:165]
	s_waitcnt vmcnt(15)
	v_lshlrev_b32_e32 v88, 16, v198
	v_and_b32_e32 v89, 0xffff0000, v198
	v_lshlrev_b32_e32 v90, 16, v199
	v_and_b32_e32 v91, 0xffff0000, v199
	v_lshlrev_b32_e32 v92, 16, v200
	v_and_b32_e32 v93, 0xffff0000, v200
	v_lshlrev_b32_e32 v94, 16, v201
	v_and_b32_e32 v95, 0xffff0000, v201
	v_pk_fma_f32 v[84:85], v[84:85], v[124:125], v[88:89]
	v_pk_fma_f32 v[88:89], v[78:79], v[122:123], v[94:95]
	v_pk_fma_f32 v[78:79], v[76:77], v[120:121], v[92:93]
	v_pk_fma_f32 v[86:87], v[86:87], v[126:127], v[90:91]
	v_cvt_pk_bf16_f32 v76, v84, v85
	s_nop 0
	v_cvt_pk_bf16_f32 v77, v86, v87
	v_cvt_pk_bf16_f32 v78, v78, v79
	v_cvt_pk_bf16_f32 v79, v88, v89
	global_store_dwordx4 v[112:113], v[76:79], off offset:256
	s_nop 0
	s_waitcnt vmcnt(15)
	v_lshlrev_b32_e32 v84, 16, v202
	v_and_b32_e32 v85, 0xffff0000, v202
	v_lshlrev_b32_e32 v76, 16, v203
	v_and_b32_e32 v77, 0xffff0000, v203
	v_lshlrev_b32_e32 v86, 16, v204
	v_and_b32_e32 v87, 0xffff0000, v204
	v_lshlrev_b32_e32 v78, 16, v205
	v_and_b32_e32 v79, 0xffff0000, v205
	v_pk_fma_f32 v[76:77], v[82:83], v[134:135], v[76:77]
	v_pk_fma_f32 v[78:79], v[74:75], v[130:131], v[78:79]
	v_pk_fma_f32 v[74:75], v[72:73], v[128:129], v[86:87]
	v_pk_fma_f32 v[80:81], v[80:81], v[132:133], v[84:85]
	s_nop 0
	v_cvt_pk_bf16_f32 v72, v80, v81
	v_cvt_pk_bf16_f32 v73, v76, v77
	v_cvt_pk_bf16_f32 v74, v74, v75
	v_cvt_pk_bf16_f32 v75, v78, v79
	s_nop 0
	v_add_co_u32_e32 v80, vcc, s69, v160
	global_store_dwordx4 v[96:97], v[72:75], off
	s_nop 0
	v_addc_co_u32_e32 v81, vcc, 0, v161, vcc
	s_waitcnt vmcnt(15)
	v_lshlrev_b32_e32 v72, 16, v206
	v_and_b32_e32 v73, 0xffff0000, v206
	v_lshlrev_b32_e32 v74, 16, v207
	v_and_b32_e32 v75, 0xffff0000, v207
	v_lshlrev_b32_e32 v76, 16, v208
	v_and_b32_e32 v77, 0xffff0000, v208
	v_lshlrev_b32_e32 v78, 16, v209
	v_and_b32_e32 v79, 0xffff0000, v209
	v_pk_fma_f32 v[68:69], v[68:69], v[124:125], v[72:73]
	v_pk_fma_f32 v[72:73], v[66:67], v[122:123], v[78:79]
	v_pk_fma_f32 v[66:67], v[64:65], v[120:121], v[76:77]
	v_pk_fma_f32 v[70:71], v[70:71], v[126:127], v[74:75]
	v_cvt_pk_bf16_f32 v64, v68, v69
	v_lshl_add_u64 v[68:69], v[160:161], 0, s[8:9]
	v_cvt_pk_bf16_f32 v65, v70, v71
	v_cvt_pk_bf16_f32 v66, v66, v67
	v_cvt_pk_bf16_f32 v67, v72, v73
	global_store_dwordx4 v[96:97], v[64:67], off offset:256
	s_nop 0
	s_waitcnt vmcnt(15)
	v_lshlrev_b32_e32 v70, 16, v210
	v_and_b32_e32 v71, 0xffff0000, v210
	v_lshlrev_b32_e32 v64, 16, v211
	v_and_b32_e32 v65, 0xffff0000, v211
	v_lshlrev_b32_e32 v72, 16, v212
	v_and_b32_e32 v73, 0xffff0000, v212
	v_lshlrev_b32_e32 v66, 16, v213
	v_and_b32_e32 v67, 0xffff0000, v213
	v_pk_fma_f32 v[62:63], v[62:63], v[134:135], v[64:65]
	v_pk_fma_f32 v[60:61], v[60:61], v[132:133], v[70:71]
	v_pk_fma_f32 v[64:65], v[58:59], v[130:131], v[66:67]
	v_pk_fma_f32 v[58:59], v[56:57], v[128:129], v[72:73]
	v_cvt_pk_bf16_f32 v56, v60, v61
	v_cvt_pk_bf16_f32 v57, v62, v63
	s_nop 0
	v_cvt_pk_bf16_f32 v58, v58, v59
	v_cvt_pk_bf16_f32 v59, v64, v65
	s_nop 0
	v_add_co_u32_e32 v64, vcc, s70, v160
	global_store_dwordx4 v[80:81], v[56:59], off
	s_nop 0
	v_addc_co_u32_e32 v65, vcc, 0, v161, vcc
	s_waitcnt vmcnt(15)
	v_lshlrev_b32_e32 v56, 16, v214
	v_and_b32_e32 v57, 0xffff0000, v214
	v_lshlrev_b32_e32 v58, 16, v215
	v_and_b32_e32 v59, 0xffff0000, v215
	v_lshlrev_b32_e32 v60, 16, v216
	v_and_b32_e32 v61, 0xffff0000, v216
	v_lshlrev_b32_e32 v62, 16, v217
	v_and_b32_e32 v63, 0xffff0000, v217
	v_pk_fma_f32 v[52:53], v[52:53], v[124:125], v[56:57]
	v_pk_fma_f32 v[56:57], v[46:47], v[122:123], v[62:63]
	v_pk_fma_f32 v[46:47], v[44:45], v[120:121], v[60:61]
	v_pk_fma_f32 v[54:55], v[54:55], v[126:127], v[58:59]
	v_cvt_pk_bf16_f32 v44, v52, v53
	v_lshl_add_u64 v[52:53], v[160:161], 0, s[18:19]
	v_cvt_pk_bf16_f32 v45, v54, v55
	v_cvt_pk_bf16_f32 v46, v46, v47
	v_cvt_pk_bf16_f32 v47, v56, v57
	global_store_dwordx4 v[68:69], v[44:47], off offset:256
	s_nop 0
	s_waitcnt vmcnt(15)
; __device__ __forceinline__ unsigned cvt_pk_bf16(float lo, float hi) { unsigned r; asm volatile("v_cvt_pk_bf16_f32 %0, %1, %2" : "=v"(r) : "v"(lo), "v"(hi)); return r; }
; #define PG8_BAR __builtin_amdgcn_s_barrier()
; template <class Epi, class Sched, bool ALIGN_EPI = false, bool SP2 = false>
; __device__ __forceinline__ void gemm_phase(PG8_LAS unsigned char* lds, const Gemm g, const Sched& S, const Epi& E) {
;     ...
;         if (!has_next) break;
; #pragma unroll
;         for (int a = 0; a < 2; ++a)
; #pragma unroll
;             for (int b = 0; b < 2; ++b)
; #pragma unroll
;                 for (int m = 0; m < 4; ++m)
; #pragma unroll
;                     for (int n = 0; n < 2; ++n) acc[a][b][m][n] = (f32x4){0.f, 0.f, 0.f, 0.f};
;         cur = nxt; cA = nA; cB = nB; ++ui;
;         if constexpr (ALIGN_EPI) { if (wr == 1) PG8_BAR; }
;     __device__ __forceinline__ void operator()(const f32x4 (&acc)[2][2][4][2], const Unit& u, int wr, int wc, int fr, int fq) const {
;     ...
;         for (int ai = 0; ai < 2; ++ai)
; #pragma unroll
;             for (int m = 0; m < 4; ++m) { const size_t off = (size_t)(row0 + ai * HALF + m * 16) * ldc + col0;
; #pragma unroll
;                 for (int bj = 0; bj < 2; ++bj) { f32x4 r0, r1;
;                     if constexpr (sizeof(TI) == 4) { r0 = *(const f32x4*)((const float*)res + off + bj * HALF); r1 = *(const f32x4*)((const float*)res + off + bj * HALF + 4); }
;                     else { const u32x4 w = *(const u32x4*)((const bf16_t*)res + off + bj * HALF);
;                         r0 = (f32x4){__uint_as_float(w.x << 16), __uint_as_float(w.x & 0xffff0000u), __uint_as_float(w.y << 16), __uint_as_float(w.y & 0xffff0000u)};
;                         r1 = (f32x4){__uint_as_float(w.z << 16), __uint_as_float(w.z & 0xffff0000u), __uint_as_float(w.w << 16), __uint_as_float(w.w & 0xffff0000u)}; }
;                     const f32x4 o0 = r0 + gv[bj][0] * acc[ai][bj][m][0], o1 = r1 + gv[bj][1] * acc[ai][bj][m][1];
;                     if constexpr (sizeof(TO) == 4) { *(f32x4*)((float*)out + off + bj * HALF) = o0; *(f32x4*)((float*)out + off + bj * HALF + 4) = o1; }
;                     else { u32x4 w; w.x = cvt_pk_bf16(o0[0], o0[1]); w.y = cvt_pk_bf16(o0[2], o0[3]); w.z = cvt_pk_bf16(o1[0], o1[1]); w.w = cvt_pk_bf16(o1[2], o1[3]); *(u32x4*)((bf16_t*)out + off + bj * HALF) = w; } }
;                 asm volatile("" ::: "memory"); }
	v_lshlrev_b32_e32 v54, 16, v226
	v_and_b32_e32 v55, 0xffff0000, v226
	v_lshlrev_b32_e32 v44, 16, v227
	v_and_b32_e32 v45, 0xffff0000, v227
	v_lshlrev_b32_e32 v56, 16, v228
	v_and_b32_e32 v57, 0xffff0000, v228
	v_lshlrev_b32_e32 v46, 16, v229
	v_and_b32_e32 v47, 0xffff0000, v229
	v_pk_fma_f32 v[44:45], v[50:51], v[134:135], v[44:45]
	v_pk_fma_f32 v[46:47], v[42:43], v[130:131], v[46:47]
	v_pk_fma_f32 v[42:43], v[40:41], v[128:129], v[56:57]
	v_pk_fma_f32 v[48:49], v[48:49], v[132:133], v[54:55]
	s_nop 0
	v_cvt_pk_bf16_f32 v40, v48, v49
	v_cvt_pk_bf16_f32 v41, v44, v45
	v_cvt_pk_bf16_f32 v42, v42, v43
	v_cvt_pk_bf16_f32 v43, v46, v47
	s_nop 0
	v_add_co_u32_e32 v48, vcc, s71, v160
	global_store_dwordx4 v[64:65], v[40:43], off
	s_nop 0
	v_addc_co_u32_e32 v49, vcc, 0, v161, vcc
	s_waitcnt vmcnt(15)
	v_lshlrev_b32_e32 v40, 16, v230
	v_and_b32_e32 v41, 0xffff0000, v230
	v_lshlrev_b32_e32 v42, 16, v231
	v_and_b32_e32 v43, 0xffff0000, v231
	v_lshlrev_b32_e32 v44, 16, v232
	v_and_b32_e32 v45, 0xffff0000, v232
	v_lshlrev_b32_e32 v46, 16, v233
	v_and_b32_e32 v47, 0xffff0000, v233
	v_pk_fma_f32 v[36:37], v[36:37], v[124:125], v[40:41]
	v_pk_fma_f32 v[40:41], v[30:31], v[122:123], v[46:47]
	v_pk_fma_f32 v[30:31], v[28:29], v[120:121], v[44:45]
	v_pk_fma_f32 v[38:39], v[38:39], v[126:127], v[42:43]
	v_cvt_pk_bf16_f32 v28, v36, v37
	v_lshl_add_u64 v[36:37], v[160:161], 0, s[20:21]
	v_cvt_pk_bf16_f32 v29, v38, v39
	v_cvt_pk_bf16_f32 v30, v30, v31
	v_cvt_pk_bf16_f32 v31, v40, v41
	global_store_dwordx4 v[52:53], v[28:31], off offset:256
	s_nop 0
	s_waitcnt vmcnt(15)
	v_lshlrev_b32_e32 v38, 16, v234
	v_and_b32_e32 v39, 0xffff0000, v234
	v_lshlrev_b32_e32 v28, 16, v235
	v_and_b32_e32 v29, 0xffff0000, v235
	v_lshlrev_b32_e32 v40, 16, v236
	v_and_b32_e32 v41, 0xffff0000, v236
	v_lshlrev_b32_e32 v30, 16, v237
	v_and_b32_e32 v31, 0xffff0000, v237
	v_pk_fma_f32 v[28:29], v[34:35], v[134:135], v[28:29]
	v_pk_fma_f32 v[30:31], v[26:27], v[130:131], v[30:31]
	v_pk_fma_f32 v[26:27], v[24:25], v[128:129], v[40:41]
	v_pk_fma_f32 v[32:33], v[32:33], v[132:133], v[38:39]
	s_nop 0
	v_cvt_pk_bf16_f32 v24, v32, v33
	v_cvt_pk_bf16_f32 v25, v28, v29
	v_cvt_pk_bf16_f32 v26, v26, v27
	v_cvt_pk_bf16_f32 v27, v30, v31
	s_nop 0
	v_add_co_u32_e32 v32, vcc, s72, v160
	global_store_dwordx4 v[48:49], v[24:27], off
	s_nop 0
	v_addc_co_u32_e32 v33, vcc, 0, v161, vcc
	s_andn2_b64 vcc, exec, s[6:7]
	s_mov_b64 s[6:7], -1
	s_waitcnt vmcnt(15)
	v_lshlrev_b32_e32 v24, 16, v238
	v_and_b32_e32 v25, 0xffff0000, v238
	v_lshlrev_b32_e32 v26, 16, v239
	v_and_b32_e32 v27, 0xffff0000, v239
	v_lshlrev_b32_e32 v28, 16, v240
	v_and_b32_e32 v29, 0xffff0000, v240
	v_lshlrev_b32_e32 v30, 16, v241
	v_and_b32_e32 v31, 0xffff0000, v241
	v_pk_fma_f32 v[20:21], v[20:21], v[124:125], v[24:25]
	v_pk_fma_f32 v[24:25], v[14:15], v[122:123], v[30:31]
	v_pk_fma_f32 v[14:15], v[12:13], v[120:121], v[28:29]
	v_pk_fma_f32 v[22:23], v[22:23], v[126:127], v[26:27]
	v_cvt_pk_bf16_f32 v12, v20, v21
	v_lshl_add_u64 v[20:21], v[160:161], 0, s[22:23]
	v_cvt_pk_bf16_f32 v13, v22, v23
	v_cvt_pk_bf16_f32 v14, v14, v15
	v_cvt_pk_bf16_f32 v15, v24, v25
	global_store_dwordx4 v[36:37], v[12:15], off offset:256
	s_nop 0
	s_waitcnt vmcnt(15)
	v_lshlrev_b32_e32 v22, 16, v242
	v_and_b32_e32 v23, 0xffff0000, v242
	v_lshlrev_b32_e32 v12, 16, v243
	v_and_b32_e32 v13, 0xffff0000, v243
	v_lshlrev_b32_e32 v24, 16, v244
	v_and_b32_e32 v25, 0xffff0000, v244
	v_lshlrev_b32_e32 v14, 16, v245
	v_and_b32_e32 v15, 0xffff0000, v245
	v_pk_fma_f32 v[12:13], v[18:19], v[134:135], v[12:13]
	v_pk_fma_f32 v[14:15], v[10:11], v[130:131], v[14:15]
	v_pk_fma_f32 v[10:11], v[8:9], v[128:129], v[24:25]
	v_pk_fma_f32 v[16:17], v[16:17], v[132:133], v[22:23]
	s_nop 0
	v_cvt_pk_bf16_f32 v8, v16, v17
	v_cvt_pk_bf16_f32 v9, v12, v13
	v_cvt_pk_bf16_f32 v10, v10, v11
	v_cvt_pk_bf16_f32 v11, v14, v15
	s_nop 0
	s_nop 0
	global_store_dwordx4 v[32:33], v[8:11], off
	s_waitcnt vmcnt(15)
	s_nop 0
	v_lshlrev_b32_e32 v8, 16, v246
	v_and_b32_e32 v9, 0xffff0000, v246
	v_lshlrev_b32_e32 v10, 16, v247
	v_and_b32_e32 v11, 0xffff0000, v247
	v_lshlrev_b32_e32 v12, 16, v248
	v_and_b32_e32 v13, 0xffff0000, v248
	v_lshlrev_b32_e32 v14, 16, v249
	v_and_b32_e32 v15, 0xffff0000, v249
	v_pk_fma_f32 v[4:5], v[4:5], v[124:125], v[8:9]
	v_pk_fma_f32 v[8:9], v[2:3], v[122:123], v[14:15]
	v_pk_fma_f32 v[2:3], v[0:1], v[120:121], v[12:13]
	v_pk_fma_f32 v[6:7], v[6:7], v[126:127], v[10:11]
	v_cvt_pk_bf16_f32 v0, v4, v5
	s_nop 0
	v_cvt_pk_bf16_f32 v1, v6, v7
	v_cvt_pk_bf16_f32 v2, v2, v3
	v_cvt_pk_bf16_f32 v3, v8, v9
	global_store_dwordx4 v[20:21], v[0:3], off offset:256
	s_cbranch_vccnz .LBB0_1034
	s_andn2_b64 vcc, exec, s[10:11]
	s_cbranch_vccnz .LBB0_1033
	s_barrier
	s_branch .LBB0_1033

;     __device__ __forceinline__ void operator()(const f32x4 (&acc)[2][2][4][2], const Unit& u, int wr, int wc, int fr, int fq) const {
;     ...
;         for (int ai = 0; ai < 2; ++ai)
; #pragma unroll
;             for (int m = 0; m < 4; ++m) { const size_t off = (size_t)(row0 + ai * HALF + m * 16) * ldc + col0;
; #pragma unroll
;                 for (int bj = 0; bj < 2; ++bj) { f32x4 r0, r1;
;                     if constexpr (sizeof(TI) == 4) { r0 = *(const f32x4*)((const float*)res + off + bj * HALF); r1 = *(const f32x4*)((const float*)res + off + bj * HALF + 4); }
;                     else { const u32x4 w = *(const u32x4*)((const bf16_t*)res + off + bj * HALF);
;                         r0 = (f32x4){__uint_as_float(w.x << 16), __uint_as_float(w.x & 0xffff0000u), __uint_as_float(w.y << 16), __uint_as_float(w.y & 0xffff0000u)};
;                         r1 = (f32x4){__uint_as_float(w.z << 16), __uint_as_float(w.z & 0xffff0000u), __uint_as_float(w.w << 16), __uint_as_float(w.w & 0xffff0000u)}; }
;                     const f32x4 o0 = r0 + gv[bj][0] * acc[ai][bj][m][0], o1 = r1 + gv[bj][1] * acc[ai][bj][m][1];
;                     if constexpr (sizeof(TO) == 4) { *(f32x4*)((float*)out + off + bj * HALF) = o0; *(f32x4*)((float*)out + off + bj * HALF + 4) = o1; }
.LBB0_1253:
	s_ashr_i32 s30, s69, 31
	s_lshr_b32 s30, s30, 28
	v_lshl_add_u32 v164, s69, 8, v166
	v_lshl_or_b32 v162, s70, 8, v168
	v_ashrrev_i32_e32 v165, 31, v164
	s_add_i32 s30, s69, s30
	v_ashrrev_i32_e32 v163, 31, v162
	v_lshlrev_b64 v[124:125], 11, v[164:165]
	s_ashr_i32 s30, s30, 4
	v_lshl_add_u64 v[160:161], v[124:125], 0, v[162:163]
	s_mul_hi_i32 s31, s30, 0xc000
	s_mul_i32 s30, s30, 0xc000
	v_lshl_add_u64 v[176:177], v[160:161], 1, s[12:13]
	s_add_u32 s30, s60, s30
	global_load_dwordx4 v[172:175], v[176:177], off
	s_addc_u32 s31, s61, s31
	v_lshl_add_u64 v[124:125], v[162:163], 2, s[30:31]
	global_load_dwordx4 v[136:139], v[124:125], off
	global_load_dwordx4 v[132:135], v[124:125], off offset:16
	v_lshl_add_u64 v[178:179], v[160:161], 2, s[14:15]
	global_load_dwordx4 v[140:143], v[124:125], off offset:512
	s_nop 0
	global_load_dwordx4 v[124:127], v[124:125], off offset:528
	global_load_dwordx4 v[184:187], v[176:177], off offset:256
	s_mov_b32 s92, 0x10000
	s_mov_b32 s93, 0
	v_lshl_add_u64 v[250:251], v[176:177], 0, s[92:93]
	global_load_dwordx4 v[188:191], v[250:251], off
	global_load_dwordx4 v[194:197], v[250:251], off offset:256
	s_mov_b32 s92, 0x20000
	s_mov_b32 s93, 0
	v_lshl_add_u64 v[250:251], v[176:177], 0, s[92:93]
	global_load_dwordx4 v[198:201], v[250:251], off
	global_load_dwordx4 v[202:205], v[250:251], off offset:256
	s_mov_b32 s92, 0x30000
	s_mov_b32 s93, 0
	v_lshl_add_u64 v[250:251], v[176:177], 0, s[92:93]
	global_load_dwordx4 v[206:209], v[250:251], off
	global_load_dwordx4 v[210:213], v[250:251], off offset:256
	s_mov_b32 s92, 0x80000
	s_mov_b32 s93, 0
	v_lshl_add_u64 v[250:251], v[176:177], 0, s[92:93]
	global_load_dwordx4 v[214:217], v[250:251], off
	global_load_dwordx4 v[226:229], v[250:251], off offset:256
	s_mov_b32 s92, 0x90000
	s_mov_b32 s93, 0
	v_lshl_add_u64 v[250:251], v[176:177], 0, s[92:93]
	global_load_dwordx4 v[230:233], v[250:251], off
	global_load_dwordx4 v[234:237], v[250:251], off offset:256
	s_mov_b32 s92, 0xa0000
	s_mov_b32 s93, 0
	v_lshl_add_u64 v[250:251], v[176:177], 0, s[92:93]
	global_load_dwordx4 v[238:241], v[250:251], off
	global_load_dwordx4 v[242:245], v[250:251], off offset:256
	s_mov_b32 s92, 0xb0000
	s_mov_b32 s93, 0
	v_lshl_add_u64 v[250:251], v[176:177], 0, s[92:93]
	global_load_dwordx4 v[246:249], v[250:251], off
	s_and_b64 vcc, exec, s[6:7]
	s_mov_b64 s[6:7], -1
	s_waitcnt vmcnt(14)
	v_lshlrev_b32_e32 v180, 16, v172
	v_and_b32_e32 v181, 0xffff0000, v172
	v_lshlrev_b32_e32 v172, 16, v173
	v_and_b32_e32 v173, 0xffff0000, v173
	v_lshlrev_b32_e32 v182, 16, v174
	v_and_b32_e32 v183, 0xffff0000, v174
	v_lshlrev_b32_e32 v174, 16, v175
	v_and_b32_e32 v175, 0xffff0000, v175
	v_pk_fma_f32 v[130:131], v[130:131], v[138:139], v[172:173]
	v_pk_fma_f32 v[128:129], v[128:129], v[136:137], v[180:181]
	v_pk_fma_f32 v[122:123], v[122:123], v[134:135], v[174:175]
	v_pk_fma_f32 v[120:121], v[120:121], v[132:133], v[182:183]
	global_store_dwordx4 v[178:179], v[128:131], off
	global_store_dwordx4 v[178:179], v[120:123], off offset:16
	s_nop 0
	v_or_b32_e32 v128, 16, v164
	v_ashrrev_i32_e32 v129, 31, v128
	v_lshlrev_b64 v[128:129], 11, v[128:129]
	v_lshl_add_u64 v[128:129], v[128:129], 0, v[162:163]
	v_lshl_add_u64 v[130:131], v[128:129], 1, s[12:13]
	s_waitcnt vmcnt(15)
	v_lshlrev_b32_e32 v172, 16, v184
	v_and_b32_e32 v173, 0xffff0000, v184
	v_lshlrev_b32_e32 v120, 16, v185
	v_and_b32_e32 v121, 0xffff0000, v185
	v_lshlrev_b32_e32 v174, 16, v186
	v_and_b32_e32 v175, 0xffff0000, v186
	v_lshlrev_b32_e32 v122, 16, v187
	v_and_b32_e32 v123, 0xffff0000, v187
	v_pk_fma_f32 v[118:119], v[118:119], v[142:143], v[120:121]
	v_pk_fma_f32 v[116:117], v[116:117], v[140:141], v[172:173]
	v_pk_fma_f32 v[114:115], v[114:115], v[126:127], v[122:123]
	v_pk_fma_f32 v[112:113], v[112:113], v[124:125], v[174:175]
	global_store_dwordx4 v[178:179], v[116:119], off offset:512
	global_store_dwordx4 v[178:179], v[112:115], off offset:528
	s_nop 0
	v_lshl_add_u64 v[116:117], v[128:129], 2, s[14:15]
	s_waitcnt vmcnt(16)
	v_lshlrev_b32_e32 v118, 16, v188
	v_and_b32_e32 v119, 0xffff0000, v188
	v_lshlrev_b32_e32 v112, 16, v189
	v_and_b32_e32 v113, 0xffff0000, v189
	v_lshlrev_b32_e32 v120, 16, v190
	v_and_b32_e32 v121, 0xffff0000, v190
	v_lshlrev_b32_e32 v114, 16, v191
	v_and_b32_e32 v115, 0xffff0000, v191
	v_pk_fma_f32 v[110:111], v[110:111], v[138:139], v[112:113]
	v_pk_fma_f32 v[108:109], v[108:109], v[136:137], v[118:119]
	v_pk_fma_f32 v[106:107], v[106:107], v[134:135], v[114:115]
	v_pk_fma_f32 v[104:105], v[104:105], v[132:133], v[120:121]
	global_store_dwordx4 v[116:117], v[108:111], off
	global_store_dwordx4 v[116:117], v[104:107], off offset:16
	s_nop 0
	v_or_b32_e32 v108, 32, v164
	v_ashrrev_i32_e32 v109, 31, v108
	v_lshlrev_b64 v[108:109], 11, v[108:109]
	v_lshl_add_u64 v[108:109], v[108:109], 0, v[162:163]
	v_lshl_add_u64 v[110:111], v[108:109], 1, s[12:13]
	s_waitcnt vmcnt(17)
	v_lshlrev_b32_e32 v112, 16, v194
	v_and_b32_e32 v113, 0xffff0000, v194
	v_lshlrev_b32_e32 v104, 16, v195
	v_and_b32_e32 v105, 0xffff0000, v195
	v_lshlrev_b32_e32 v114, 16, v196
	v_and_b32_e32 v115, 0xffff0000, v196
	v_lshlrev_b32_e32 v106, 16, v197
	v_and_b32_e32 v107, 0xffff0000, v197
	v_pk_fma_f32 v[102:103], v[102:103], v[142:143], v[104:105]
	v_pk_fma_f32 v[100:101], v[100:101], v[140:141], v[112:113]
	v_pk_fma_f32 v[98:99], v[98:99], v[126:127], v[106:107]
	v_pk_fma_f32 v[96:97], v[96:97], v[124:125], v[114:115]
	global_store_dwordx4 v[116:117], v[100:103], off offset:512
	global_store_dwordx4 v[116:117], v[96:99], off offset:528
	s_nop 0
	v_lshl_add_u64 v[100:101], v[108:109], 2, s[14:15]
	s_waitcnt vmcnt(18)
;     __device__ __forceinline__ void operator()(const f32x4 (&acc)[2][2][4][2], const Unit& u, int wr, int wc, int fr, int fq) const {
;     ...
;         for (int ai = 0; ai < 2; ++ai)
; #pragma unroll
;             for (int m = 0; m < 4; ++m) { const size_t off = (size_t)(row0 + ai * HALF + m * 16) * ldc + col0;
; #pragma unroll
;                 for (int bj = 0; bj < 2; ++bj) { f32x4 r0, r1;
;                     if constexpr (sizeof(TI) == 4) { r0 = *(const f32x4*)((const float*)res + off + bj * HALF); r1 = *(const f32x4*)((const float*)res + off + bj * HALF + 4); }
;                     else { const u32x4 w = *(const u32x4*)((const bf16_t*)res + off + bj * HALF);
;                         r0 = (f32x4){__uint_as_float(w.x << 16), __uint_as_float(w.x & 0xffff0000u), __uint_as_float(w.y << 16), __uint_as_float(w.y & 0xffff0000u)};
;                         r1 = (f32x4){__uint_as_float(w.z << 16), __uint_as_float(w.z & 0xffff0000u), __uint_as_float(w.w << 16), __uint_as_float(w.w & 0xffff0000u)}; }
;                     const f32x4 o0 = r0 + gv[bj][0] * acc[ai][bj][m][0], o1 = r1 + gv[bj][1] * acc[ai][bj][m][1];
;                     if constexpr (sizeof(TO) == 4) { *(f32x4*)((float*)out + off + bj * HALF) = o0; *(f32x4*)((float*)out + off + bj * HALF + 4) = o1; }
	v_lshlrev_b32_e32 v102, 16, v198
	v_and_b32_e32 v103, 0xffff0000, v198
	v_lshlrev_b32_e32 v96, 16, v199
	v_and_b32_e32 v97, 0xffff0000, v199
	v_lshlrev_b32_e32 v104, 16, v200
	v_and_b32_e32 v105, 0xffff0000, v200
	v_lshlrev_b32_e32 v98, 16, v201
	v_and_b32_e32 v99, 0xffff0000, v201
	v_pk_fma_f32 v[94:95], v[94:95], v[138:139], v[96:97]
	v_pk_fma_f32 v[92:93], v[92:93], v[136:137], v[102:103]
	v_pk_fma_f32 v[90:91], v[90:91], v[134:135], v[98:99]
	v_pk_fma_f32 v[88:89], v[88:89], v[132:133], v[104:105]
	global_store_dwordx4 v[100:101], v[92:95], off
	global_store_dwordx4 v[100:101], v[88:91], off offset:16
	s_nop 0
	v_or_b32_e32 v92, 48, v164
	v_ashrrev_i32_e32 v93, 31, v92
	v_lshlrev_b64 v[92:93], 11, v[92:93]
	v_lshl_add_u64 v[92:93], v[92:93], 0, v[162:163]
	v_lshl_add_u64 v[94:95], v[92:93], 1, s[12:13]
	s_waitcnt vmcnt(19)
	v_lshlrev_b32_e32 v96, 16, v202
	v_and_b32_e32 v97, 0xffff0000, v202
	v_lshlrev_b32_e32 v88, 16, v203
	v_and_b32_e32 v89, 0xffff0000, v203
	v_lshlrev_b32_e32 v98, 16, v204
	v_and_b32_e32 v99, 0xffff0000, v204
	v_lshlrev_b32_e32 v90, 16, v205
	v_and_b32_e32 v91, 0xffff0000, v205
	v_pk_fma_f32 v[86:87], v[86:87], v[142:143], v[88:89]
	v_pk_fma_f32 v[84:85], v[84:85], v[140:141], v[96:97]
	v_pk_fma_f32 v[82:83], v[82:83], v[126:127], v[90:91]
	v_pk_fma_f32 v[80:81], v[80:81], v[124:125], v[98:99]
	global_store_dwordx4 v[100:101], v[84:87], off offset:512
	global_store_dwordx4 v[100:101], v[80:83], off offset:528
	s_nop 0
	v_lshl_add_u64 v[84:85], v[92:93], 2, s[14:15]
	s_waitcnt vmcnt(20)
	v_lshlrev_b32_e32 v86, 16, v206
	v_and_b32_e32 v87, 0xffff0000, v206
	v_lshlrev_b32_e32 v80, 16, v207
	v_and_b32_e32 v81, 0xffff0000, v207
	v_lshlrev_b32_e32 v88, 16, v208
	v_and_b32_e32 v89, 0xffff0000, v208
	v_lshlrev_b32_e32 v82, 16, v209
	v_and_b32_e32 v83, 0xffff0000, v209
	v_pk_fma_f32 v[78:79], v[78:79], v[138:139], v[80:81]
	v_pk_fma_f32 v[76:77], v[76:77], v[136:137], v[86:87]
	v_pk_fma_f32 v[74:75], v[74:75], v[134:135], v[82:83]
	v_pk_fma_f32 v[72:73], v[72:73], v[132:133], v[88:89]
	global_store_dwordx4 v[84:85], v[76:79], off
	global_store_dwordx4 v[84:85], v[72:75], off offset:16
	s_nop 0
	v_lshl_add_u64 v[76:77], v[160:161], 0, s[20:21]
	v_lshl_add_u64 v[78:79], v[76:77], 1, s[12:13]
	s_waitcnt vmcnt(21)
	v_lshlrev_b32_e32 v80, 16, v210
	v_and_b32_e32 v81, 0xffff0000, v210
	v_lshlrev_b32_e32 v72, 16, v211
	v_and_b32_e32 v73, 0xffff0000, v211
	v_lshlrev_b32_e32 v82, 16, v212
	v_and_b32_e32 v83, 0xffff0000, v212
	v_lshlrev_b32_e32 v74, 16, v213
	v_and_b32_e32 v75, 0xffff0000, v213
	v_pk_fma_f32 v[70:71], v[70:71], v[142:143], v[72:73]
	v_pk_fma_f32 v[68:69], v[68:69], v[140:141], v[80:81]
	v_pk_fma_f32 v[66:67], v[66:67], v[126:127], v[74:75]
	v_pk_fma_f32 v[64:65], v[64:65], v[124:125], v[82:83]
	global_store_dwordx4 v[84:85], v[68:71], off offset:512
	global_store_dwordx4 v[84:85], v[64:67], off offset:528
	s_nop 0
	v_lshl_add_u64 v[68:69], v[76:77], 2, s[14:15]
	s_waitcnt vmcnt(22)
	v_lshlrev_b32_e32 v70, 16, v214
	v_and_b32_e32 v71, 0xffff0000, v214
	v_lshlrev_b32_e32 v64, 16, v215
	v_and_b32_e32 v65, 0xffff0000, v215
	v_lshlrev_b32_e32 v72, 16, v216
	v_and_b32_e32 v73, 0xffff0000, v216
	v_lshlrev_b32_e32 v66, 16, v217
	v_and_b32_e32 v67, 0xffff0000, v217
	v_pk_fma_f32 v[62:63], v[62:63], v[138:139], v[64:65]
	v_pk_fma_f32 v[60:61], v[60:61], v[136:137], v[70:71]
	v_pk_fma_f32 v[58:59], v[58:59], v[134:135], v[66:67]
	v_pk_fma_f32 v[56:57], v[56:57], v[132:133], v[72:73]
	global_store_dwordx4 v[68:69], v[60:63], off
	global_store_dwordx4 v[68:69], v[56:59], off offset:16
	s_nop 0
	v_lshl_add_u64 v[60:61], v[160:161], 0, s[22:23]
	v_lshl_add_u64 v[62:63], v[60:61], 1, s[12:13]
	s_waitcnt vmcnt(23)
	v_lshlrev_b32_e32 v64, 16, v226
	v_and_b32_e32 v65, 0xffff0000, v226
	v_lshlrev_b32_e32 v56, 16, v227
	v_and_b32_e32 v57, 0xffff0000, v227
	v_lshlrev_b32_e32 v66, 16, v228
	v_and_b32_e32 v67, 0xffff0000, v228
	v_lshlrev_b32_e32 v58, 16, v229
	v_and_b32_e32 v59, 0xffff0000, v229
	v_pk_fma_f32 v[54:55], v[54:55], v[142:143], v[56:57]
	v_pk_fma_f32 v[52:53], v[52:53], v[140:141], v[64:65]
	v_pk_fma_f32 v[50:51], v[50:51], v[126:127], v[58:59]
	v_pk_fma_f32 v[48:49], v[48:49], v[124:125], v[66:67]
	global_store_dwordx4 v[68:69], v[52:55], off offset:512
	global_store_dwordx4 v[68:69], v[48:51], off offset:528
	s_nop 0
	v_lshl_add_u64 v[52:53], v[60:61], 2, s[14:15]
	s_waitcnt vmcnt(24)
; #define PG8_BAR __builtin_amdgcn_s_barrier()
; template <class Epi, class Sched, bool ALIGN_EPI = false, bool SP2 = false>
; __device__ __forceinline__ void gemm_phase(PG8_LAS unsigned char* lds, const Gemm g, const Sched& S, const Epi& E) {
;     ...
;         if (!has_next) break;
; #pragma unroll
;         for (int a = 0; a < 2; ++a)
; #pragma unroll
;             for (int b = 0; b < 2; ++b)
; #pragma unroll
;                 for (int m = 0; m < 4; ++m)
; #pragma unroll
;                     for (int n = 0; n < 2; ++n) acc[a][b][m][n] = (f32x4){0.f, 0.f, 0.f, 0.f};
;         cur = nxt; cA = nA; cB = nB; ++ui;
;         if constexpr (ALIGN_EPI) { if (wr == 1) PG8_BAR; }
;     __device__ __forceinline__ void operator()(const f32x4 (&acc)[2][2][4][2], const Unit& u, int wr, int wc, int fr, int fq) const {
;     ...
;         for (int ai = 0; ai < 2; ++ai)
; #pragma unroll
;             for (int m = 0; m < 4; ++m) { const size_t off = (size_t)(row0 + ai * HALF + m * 16) * ldc + col0;
; #pragma unroll
;                 for (int bj = 0; bj < 2; ++bj) { f32x4 r0, r1;
;                     if constexpr (sizeof(TI) == 4) { r0 = *(const f32x4*)((const float*)res + off + bj * HALF); r1 = *(const f32x4*)((const float*)res + off + bj * HALF + 4); }
;                     else { const u32x4 w = *(const u32x4*)((const bf16_t*)res + off + bj * HALF);
;                         r0 = (f32x4){__uint_as_float(w.x << 16), __uint_as_float(w.x & 0xffff0000u), __uint_as_float(w.y << 16), __uint_as_float(w.y & 0xffff0000u)};
;                         r1 = (f32x4){__uint_as_float(w.z << 16), __uint_as_float(w.z & 0xffff0000u), __uint_as_float(w.w << 16), __uint_as_float(w.w & 0xffff0000u)}; }
;                     const f32x4 o0 = r0 + gv[bj][0] * acc[ai][bj][m][0], o1 = r1 + gv[bj][1] * acc[ai][bj][m][1];
;                     if constexpr (sizeof(TO) == 4) { *(f32x4*)((float*)out + off + bj * HALF) = o0; *(f32x4*)((float*)out + off + bj * HALF + 4) = o1; }
	v_lshlrev_b32_e32 v54, 16, v230
	v_and_b32_e32 v55, 0xffff0000, v230
	v_lshlrev_b32_e32 v48, 16, v231
	v_and_b32_e32 v49, 0xffff0000, v231
	v_lshlrev_b32_e32 v56, 16, v232
	v_and_b32_e32 v57, 0xffff0000, v232
	v_lshlrev_b32_e32 v50, 16, v233
	v_and_b32_e32 v51, 0xffff0000, v233
	v_pk_fma_f32 v[46:47], v[46:47], v[138:139], v[48:49]
	v_pk_fma_f32 v[44:45], v[44:45], v[136:137], v[54:55]
	v_pk_fma_f32 v[42:43], v[42:43], v[134:135], v[50:51]
	v_pk_fma_f32 v[40:41], v[40:41], v[132:133], v[56:57]
	global_store_dwordx4 v[52:53], v[44:47], off
	global_store_dwordx4 v[52:53], v[40:43], off offset:16
	s_nop 0
	v_lshl_add_u64 v[44:45], v[160:161], 0, s[24:25]
	v_lshl_add_u64 v[46:47], v[44:45], 1, s[12:13]
	s_waitcnt vmcnt(25)
	v_lshlrev_b32_e32 v48, 16, v234
	v_and_b32_e32 v49, 0xffff0000, v234
	v_lshlrev_b32_e32 v40, 16, v235
	v_and_b32_e32 v41, 0xffff0000, v235
	v_lshlrev_b32_e32 v50, 16, v236
	v_and_b32_e32 v51, 0xffff0000, v236
	v_lshlrev_b32_e32 v42, 16, v237
	v_and_b32_e32 v43, 0xffff0000, v237
	v_pk_fma_f32 v[38:39], v[38:39], v[142:143], v[40:41]
	v_pk_fma_f32 v[36:37], v[36:37], v[140:141], v[48:49]
	v_pk_fma_f32 v[34:35], v[34:35], v[126:127], v[42:43]
	v_pk_fma_f32 v[32:33], v[32:33], v[124:125], v[50:51]
	global_store_dwordx4 v[52:53], v[36:39], off offset:512
	global_store_dwordx4 v[52:53], v[32:35], off offset:528
	s_nop 0
	v_lshl_add_u64 v[36:37], v[44:45], 2, s[14:15]
	s_waitcnt vmcnt(26)
	v_lshlrev_b32_e32 v38, 16, v238
	v_and_b32_e32 v39, 0xffff0000, v238
	v_lshlrev_b32_e32 v32, 16, v239
	v_and_b32_e32 v33, 0xffff0000, v239
	v_lshlrev_b32_e32 v40, 16, v240
	v_and_b32_e32 v41, 0xffff0000, v240
	v_lshlrev_b32_e32 v34, 16, v241
	v_and_b32_e32 v35, 0xffff0000, v241
	v_pk_fma_f32 v[30:31], v[30:31], v[138:139], v[32:33]
	v_pk_fma_f32 v[28:29], v[28:29], v[136:137], v[38:39]
	v_pk_fma_f32 v[26:27], v[26:27], v[134:135], v[34:35]
	v_pk_fma_f32 v[24:25], v[24:25], v[132:133], v[40:41]
	global_store_dwordx4 v[36:37], v[28:31], off
	global_store_dwordx4 v[36:37], v[24:27], off offset:16
	s_nop 0
	v_lshl_add_u64 v[28:29], v[160:161], 0, s[26:27]
	v_lshl_add_u64 v[30:31], v[28:29], 1, s[12:13]
	s_waitcnt vmcnt(27)
	v_lshlrev_b32_e32 v32, 16, v242
	v_and_b32_e32 v33, 0xffff0000, v242
	v_lshlrev_b32_e32 v24, 16, v243
	v_and_b32_e32 v25, 0xffff0000, v243
	v_lshlrev_b32_e32 v34, 16, v244
	v_and_b32_e32 v35, 0xffff0000, v244
	v_lshlrev_b32_e32 v26, 16, v245
	v_and_b32_e32 v27, 0xffff0000, v245
	v_pk_fma_f32 v[22:23], v[22:23], v[142:143], v[24:25]
	v_pk_fma_f32 v[20:21], v[20:21], v[140:141], v[32:33]
	v_pk_fma_f32 v[18:19], v[18:19], v[126:127], v[26:27]
	v_pk_fma_f32 v[16:17], v[16:17], v[124:125], v[34:35]
	global_store_dwordx4 v[36:37], v[20:23], off offset:512
	global_store_dwordx4 v[36:37], v[16:19], off offset:528
	s_nop 0
	v_lshl_add_u64 v[20:21], v[28:29], 2, s[14:15]
	s_waitcnt vmcnt(28)
	v_lshlrev_b32_e32 v22, 16, v246
	v_and_b32_e32 v23, 0xffff0000, v246
	v_lshlrev_b32_e32 v16, 16, v247
	v_and_b32_e32 v17, 0xffff0000, v247
	v_lshlrev_b32_e32 v24, 16, v248
	v_and_b32_e32 v25, 0xffff0000, v248
	v_lshlrev_b32_e32 v18, 16, v249
	v_and_b32_e32 v19, 0xffff0000, v249
	v_pk_fma_f32 v[14:15], v[14:15], v[138:139], v[16:17]
	v_pk_fma_f32 v[12:13], v[12:13], v[136:137], v[22:23]
	v_pk_fma_f32 v[10:11], v[10:11], v[134:135], v[18:19]
	v_pk_fma_f32 v[8:9], v[8:9], v[132:133], v[24:25]
	global_store_dwordx4 v[20:21], v[12:15], off
	global_store_dwordx4 v[20:21], v[8:11], off offset:16
	global_load_dwordx4 v[8:11], v[30:31], off offset:256
	s_waitcnt vmcnt(0)
	v_lshlrev_b32_e32 v12, 16, v8
	v_and_b32_e32 v13, 0xffff0000, v8
	v_lshlrev_b32_e32 v8, 16, v9
	v_and_b32_e32 v9, 0xffff0000, v9
	v_lshlrev_b32_e32 v14, 16, v10
	v_and_b32_e32 v15, 0xffff0000, v10
	v_lshlrev_b32_e32 v10, 16, v11
	v_and_b32_e32 v11, 0xffff0000, v11
	v_pk_fma_f32 v[6:7], v[6:7], v[142:143], v[8:9]
	v_pk_fma_f32 v[4:5], v[4:5], v[140:141], v[12:13]
	v_pk_fma_f32 v[2:3], v[2:3], v[126:127], v[10:11]
	v_pk_fma_f32 v[0:1], v[0:1], v[124:125], v[14:15]
	global_store_dwordx4 v[20:21], v[4:7], off offset:512
	global_store_dwordx4 v[20:21], v[0:3], off offset:528
	s_cbranch_vccnz .LBB0_1238
	s_andn2_b64 vcc, exec, s[10:11]
	s_cbranch_vccnz .LBB0_1237
	s_barrier
	s_branch .LBB0_1237

; __global__ void __launch_bounds__(NTHR, 2) fwd_kernel(Args args) {
	.amdhsa_kernel _Z10fwd_kernel4Args
		.amdhsa_group_segment_fixed_size 0
		.amdhsa_private_segment_fixed_size 0
		.amdhsa_kernarg_size 440
		.amdhsa_user_sgpr_count 2
		.amdhsa_user_sgpr_dispatch_ptr 0
		.amdhsa_user_sgpr_queue_ptr 0
		.amdhsa_user_sgpr_kernarg_segment_ptr 1
		.amdhsa_user_sgpr_dispatch_id 0
		.amdhsa_user_sgpr_kernarg_preload_length 0
		.amdhsa_user_sgpr_kernarg_preload_offset 0
		.amdhsa_user_sgpr_private_segment_size 0
		.amdhsa_uses_dynamic_stack 0
		.amdhsa_enable_private_segment 0
		.amdhsa_system_sgpr_workgroup_id_x 1
		.amdhsa_system_sgpr_workgroup_id_y 0
		.amdhsa_system_sgpr_workgroup_id_z 0
		.amdhsa_system_sgpr_workgroup_info 0
		.amdhsa_system_vgpr_workitem_id 2
		.amdhsa_next_free_vgpr 252
		.amdhsa_next_free_sgpr 96
		.amdhsa_accum_offset 252
		.amdhsa_reserve_vcc 1
		.amdhsa_float_round_mode_32 0
		.amdhsa_float_round_mode_16_64 0
		.amdhsa_float_denorm_mode_32 3
		.amdhsa_float_denorm_mode_16_64 3
		.amdhsa_dx10_clamp 1
		.amdhsa_ieee_mode 1
		.amdhsa_fp16_overflow 0
		.amdhsa_tg_split 0
		.amdhsa_exception_fp_ieee_invalid_op 0
		.amdhsa_exception_fp_denorm_src 0
		.amdhsa_exception_fp_ieee_div_zero 0
		.amdhsa_exception_fp_ieee_overflow 0
		.amdhsa_exception_fp_ieee_underflow 0
		.amdhsa_exception_fp_ieee_inexact 0
		.amdhsa_exception_int_div_zero 0
	.end_amdhsa_kernel

; __global__ void __launch_bounds__(NTHR, 2) fwd_kernel(Args args) {
amdhsa.kernels:
  - .agpr_count:     0
    .args:
      - .offset:         0
        .size:           184
        .value_kind:     by_value
      - .offset:         184
        .size:           4
        .value_kind:     hidden_block_count_x
      - .offset:         188
        .size:           4
        .value_kind:     hidden_block_count_y
      - .offset:         192
        .size:           4
        .value_kind:     hidden_block_count_z
      - .offset:         196
        .size:           2
        .value_kind:     hidden_group_size_x
      - .offset:         198
        .size:           2
        .value_kind:     hidden_group_size_y
      - .offset:         200
        .size:           2
        .value_kind:     hidden_group_size_z
      - .offset:         202
        .size:           2
        .value_kind:     hidden_remainder_x
      - .offset:         204
        .size:           2
        .value_kind:     hidden_remainder_y
      - .offset:         206
        .size:           2
        .value_kind:     hidden_remainder_z
      - .offset:         224
        .size:           8
        .value_kind:     hidden_global_offset_x
      - .offset:         232
        .size:           8
        .value_kind:     hidden_global_offset_y
      - .offset:         240
        .size:           8
        .value_kind:     hidden_global_offset_z
      - .offset:         248
        .size:           2
        .value_kind:     hidden_grid_dims
      - .offset:         272
        .size:           8
        .value_kind:     hidden_multigrid_sync_arg
      - .offset:         304
        .size:           4
        .value_kind:     hidden_dynamic_lds_size
    .group_segment_fixed_size: 0
    .kernarg_segment_align: 8
    .kernarg_segment_size: 440
    .language:       OpenCL C
    .language_version:
      - 2
      - 0
    .max_flat_workgroup_size: 512
    .name:           _Z10fwd_kernel4Args
    .private_segment_fixed_size: 0
    .sgpr_count:     102
    .sgpr_spill_count: 0
    .symbol:         _Z10fwd_kernel4Args.kd
    .uniform_work_group_size: 1
    .uses_dynamic_stack: false
    .vgpr_count:     252
    .vgpr_spill_count: 0
    .wavefront_size: 64
